# v024 + hand-written workgroup-collective copy engines at the P2/P5/P7 idle workgroups: arrival poll and next grab's atomic in flight behind the copy loads, stores not waited, one barrier per grab
# speedup vs baseline: 1.0107x; 1.0107x over previous
.LBB0_175:
	s_nop 0
	v_readlane_b32 s4, v242, 2
	v_readlane_b32 s6, v242, 4
	v_readlane_b32 s7, v242, 5
	s_add_u32 s0, s6, 0x2000
	s_addc_u32 s1, s7, 0
	v_readlane_b32 s5, v242, 3
	v_writelane_b32 v242, s0, 43
	v_lshlrev_b32_e32 v148, 4, v0
	s_nop 0
	v_writelane_b32 v242, s1, 44
	s_add_u32 s0, s6, 0x6200000
	s_addc_u32 s1, s7, 0
	v_writelane_b32 v242, s0, 45
	s_nop 1
	v_writelane_b32 v242, s1, 46
	s_add_u32 s0, s6, 0xa400000
	s_addc_u32 s1, s7, 0
	v_writelane_b32 v242, s0, 47
	s_nop 1
	v_writelane_b32 v242, s1, 48
	s_add_u32 s0, s6, 0x2d500000
	s_addc_u32 s1, s7, 0
	v_writelane_b32 v242, s0, 49
	s_nop 1
	v_writelane_b32 v242, s1, 50
	s_add_u32 s0, s6, 0x2f600000
	s_addc_u32 s1, s7, 0
	v_writelane_b32 v242, s0, 51
	s_nop 1
	v_writelane_b32 v242, s1, 52
	s_add_u32 s0, s6, 0x31700000
	s_addc_u32 s1, s7, 0
	s_cmpk_eq_i32 s84, 0x100
	v_writelane_b32 v242, s0, 53
	s_cselect_b64 s[58:59], -1, 0
	s_cmp_lt_i32 s72, 3
	v_writelane_b32 v242, s1, 54
	s_cselect_b64 s[0:1], -1, 0
	s_cmp_gt_i32 s73, 2
	s_cselect_b64 s[2:3], -1, 0
	s_and_b64 s[0:1], s[0:1], s[2:3]
	v_writelane_b32 v242, s92, 55
	s_andn2_b64 vcc, exec, s[0:1]
	s_mov_b32 s0, s84
	v_writelane_b32 v242, s93, 56
	v_writelane_b32 v242, s0, 57
	v_writelane_b32 v241, s58, 0
	s_nop 0
	v_writelane_b32 v242, s1, 58
	v_writelane_b32 v242, s72, 59
	s_mov_b32 s0, s88
	v_writelane_b32 v241, s59, 1
	v_writelane_b32 v242, s73, 60
	v_writelane_b32 v242, s0, 61
	s_nop 1
	v_writelane_b32 v242, s1, 62
	v_writelane_b32 v242, s74, 63
	s_cbranch_vccnz .LBB0_607
	s_and_b64 s[0:1], s[58:59], exec
	s_cselect_b32 s33, 0xd8, s84
	s_add_u32 s0, s6, 0x5400
	s_addc_u32 s1, s7, 0
	v_writelane_b32 v241, s0, 2
	v_mov_b32_e32 v149, 0
	v_lshl_add_u64 v[152:153], s[4:5], 0, v[148:149]
	v_writelane_b32 v241, s1, 3
	s_add_u32 s0, s6, 0x5500
	s_addc_u32 s1, s7, 0
	v_writelane_b32 v241, s0, 4
	s_nop 1
	v_writelane_b32 v241, s1, 5
	s_add_u32 s0, s6, 0x5600
	s_addc_u32 s1, s7, 0
	v_writelane_b32 v241, s0, 6
	s_nop 1
	v_writelane_b32 v241, s1, 7
	s_add_u32 s0, s6, 0x5700
	s_addc_u32 s1, s7, 0
	v_writelane_b32 v241, s0, 8
	s_nop 1
	v_writelane_b32 v241, s1, 9
	s_add_u32 s0, s6, 0x5800
	s_addc_u32 s1, s7, 0
	v_writelane_b32 v241, s0, 10
	s_nop 1
	v_writelane_b32 v241, s1, 11
	s_add_u32 s0, s6, 0x5900
	s_addc_u32 s1, s7, 0
	s_add_u32 s34, s6, 0x5a00
	s_addc_u32 s35, s7, 0
	s_add_u32 s40, s6, 0x5b00
	s_addc_u32 s41, s7, 0
	s_add_u32 s42, s6, 0x5c00
	s_addc_u32 s43, s7, 0
	s_add_u32 s50, s6, 0x5d00
	s_addc_u32 s51, s7, 0
	s_add_u32 s56, s6, 0x5e00
	s_addc_u32 s57, s7, 0
	s_add_u32 s60, s6, 0x5f00
	s_addc_u32 s61, s7, 0
	s_add_u32 s62, s6, 0x6000
	s_addc_u32 s63, s7, 0
	s_add_u32 s64, s6, 0x6100
	s_addc_u32 s65, s7, 0
	s_add_u32 s68, s6, 0x6200
	s_addc_u32 s69, s7, 0
	s_add_u32 s70, s6, 0x6300
	s_addc_u32 s71, s7, 0
	s_ashr_i32 s54, s33, 31
	v_writelane_b32 v241, s0, 12
	s_cmp_gt_u32 s73, 3
	s_nop 0
	v_writelane_b32 v241, s1, 13
	s_cselect_b64 s[0:1], -1, 0
	v_writelane_b32 v241, s0, 14
	s_cmp_lt_i32 s92, s33
	s_nop 0
	v_writelane_b32 v241, s1, 15
	s_mov_b64 s[0:1], -1
	s_cbranch_scc1 .LBB0_210
	v_lshlrev_b32_e32 v104, 4, v0
	v_add_u32_e32 v105, 0x2000, v104
	v_add_u32_e32 v106, 0x4000, v104
	v_add_u32_e32 v107, 0x6000, v104
	v_add_u32_e32 v108, 0x8000, v104
	v_add_u32_e32 v109, 0xa000, v104
	v_add_u32_e32 v110, 0xc000, v104
	v_add_u32_e32 v111, 0xe000, v104
	v_lshrrev_b32_e32 v5, 6, v0
	v_readlane_b32 s56, v242, 43
	v_readlane_b32 s57, v242, 44
	v_readlane_b32 s60, v242, 2
	v_readlane_b32 s61, v242, 3
	v_readlane_b32 s66, v242, 4
	v_readlane_b32 s67, v242, 5
	v_readlane_b32 s68, v242, 25
	v_readfirstlane_b32 s70, v5
	v_mov_b32_e32 v2, 0
	v_mov_b32_e32 v3, 8
	v_mov_b32_e32 v6, 0x20180
	s_mov_b32 s64, 0x10478000
	s_mov_b32 s65, 0x30478000
	s_add_u32 s66, s66, 0x5400
	s_addc_u32 s67, s67, 0
	s_mul_i32 s68, s68, s84
	s_mov_b64 s[62:63], exec
	s_mov_b32 s71, 0
	s_cmp_lg_u32 s70, 0
	s_cbranch_scc1 .Lce_first_done_P2
	s_mov_b64 exec, 1
	global_atomic_add v4, v2, v3, s[56:57] sc0
	s_waitcnt vmcnt(0)
	ds_write_b32 v6, v4
	s_waitcnt lgkmcnt(0)
	s_mov_b64 exec, s[62:63]
.Lce_first_done_P2:
	s_barrier
	ds_read_b32 v7, v6
	s_waitcnt lgkmcnt(0)
	v_readfirstlane_b32 s4, v7
	s_nop 3
	s_mov_b32 s71, 1
	s_cmp_ge_u32 s4, 0x1fe00
	s_cbranch_scc1 .Lce_exit_P2
.Lce_loop_P2:
	s_cmp_lg_u32 s70, 0
	s_cbranch_scc1 .Lce_nopoll_P2
	s_mov_b64 exec, 1
	global_load_dword v8, v2, s[66:67] sc1
	global_load_dword v9, v2, s[66:67] offset:256 sc1
	global_load_dword v10, v2, s[66:67] offset:512 sc1
	global_load_dword v11, v2, s[66:67] offset:768 sc1
	global_load_dword v12, v2, s[66:67] offset:1024 sc1
	global_load_dword v13, v2, s[66:67] offset:1280 sc1
	global_load_dword v14, v2, s[66:67] offset:1536 sc1
	global_load_dword v15, v2, s[66:67] offset:1792 sc1
	global_load_dword v16, v2, s[66:67] offset:2048 sc1
	global_load_dword v17, v2, s[66:67] offset:2304 sc1
	global_load_dword v18, v2, s[66:67] offset:2560 sc1
	global_load_dword v19, v2, s[66:67] offset:2816 sc1
	global_load_dword v20, v2, s[66:67] offset:3072 sc1
	global_load_dword v21, v2, s[66:67] offset:3328 sc1
	global_load_dword v22, v2, s[66:67] offset:3584 sc1
	global_load_dword v23, v2, s[66:67] offset:3840 sc1
	s_mov_b64 exec, s[62:63]
.Lce_nopoll_P2:
	s_cmp_ge_u32 s4, 0xff00
	s_cselect_b32 s8, s46, s44
	s_cselect_b32 s9, s47, s45
	s_cselect_b32 s55, s65, s64
	s_cselect_b32 s52, 0xff00, 0
	s_sub_u32 s52, s4, s52
	s_mul_hi_i32 s53, s52, 0x80808081
	s_add_i32 s53, s53, s52
	s_lshr_b32 s54, s53, 31
	s_ashr_i32 s53, s53, 8
	s_add_i32 s53, s53, s54
	s_mul_i32 s54, s53, 0x1fe
	s_sub_u32 s54, s52, s54
	s_sub_u32 s75, 0x1fe, s54
	s_lshl_b32 s53, s53, 22
	s_lshl_b32 s54, s54, 13
	s_add_u32 s53, s53, s54
	s_add_u32 s55, s55, s53
	s_add_u32 s53, s53, 0x4000
	s_add_u32 s8, s8, s53
	s_addc_u32 s9, s9, 0
	s_add_u32 s10, s60, s55
	s_addc_u32 s11, s61, 0
	s_add_u32 s12, s8, 0x4000
	s_addc_u32 s13, s9, 0
	s_add_u32 s50, s10, 0x4000
	s_addc_u32 s51, s11, 0
	s_cmp_le_u32 s75, 0
	s_cselect_b32 s6, s12, s8
	s_cselect_b32 s7, s13, s9
	global_load_dwordx4 v[40:43], v104, s[6:7] nt
	s_cmp_le_u32 s75, 1
	s_cselect_b32 s6, s12, s8
	s_cselect_b32 s7, s13, s9
	global_load_dwordx4 v[44:47], v105, s[6:7] nt
	s_cmp_le_u32 s75, 2
	s_cselect_b32 s6, s12, s8
	s_cselect_b32 s7, s13, s9
	global_load_dwordx4 v[48:51], v106, s[6:7] nt
	s_cmp_le_u32 s75, 3
	s_cselect_b32 s6, s12, s8
	s_cselect_b32 s7, s13, s9
	global_load_dwordx4 v[52:55], v107, s[6:7] nt
	s_cmp_le_u32 s75, 4
	s_cselect_b32 s6, s12, s8
	s_cselect_b32 s7, s13, s9
	global_load_dwordx4 v[56:59], v108, s[6:7] nt
	s_cmp_le_u32 s75, 5
	s_cselect_b32 s6, s12, s8
	s_cselect_b32 s7, s13, s9
	global_load_dwordx4 v[60:63], v109, s[6:7] nt
	s_cmp_le_u32 s75, 6
	s_cselect_b32 s6, s12, s8
	s_cselect_b32 s7, s13, s9
	global_load_dwordx4 v[64:67], v110, s[6:7] nt
	s_cmp_le_u32 s75, 7
	s_cselect_b32 s6, s12, s8
	s_cselect_b32 s7, s13, s9
	global_load_dwordx4 v[68:71], v111, s[6:7] nt
	s_mov_b32 s77, -1
	s_cmp_lg_u32 s70, 0
	s_cbranch_scc1 .Lce_wait_all_P2
	s_waitcnt vmcnt(8)
	s_mov_b64 exec, 1
	v_add_u32_e32 v8, v8, v9
	v_add_u32_e32 v8, v8, v10
	v_add_u32_e32 v8, v8, v11
	v_add_u32_e32 v8, v8, v12
	v_add_u32_e32 v8, v8, v13
	v_add_u32_e32 v8, v8, v14
	v_add_u32_e32 v8, v8, v15
	v_add_u32_e32 v8, v8, v16
	v_add_u32_e32 v8, v8, v17
	v_add_u32_e32 v8, v8, v18
	v_add_u32_e32 v8, v8, v19
	v_add_u32_e32 v8, v8, v20
	v_add_u32_e32 v8, v8, v21
	v_add_u32_e32 v8, v8, v22
	v_add_u32_e32 v8, v8, v23
	s_nop 1
	v_readfirstlane_b32 s69, v8
	s_nop 3
	s_sub_u32 s69, s69, s68
	s_cmp_ge_u32 s69, 16
	s_cbranch_scc1 .Lce_stop_P2
	global_atomic_add v4, v2, v3, s[56:57] sc0
	s_mov_b64 exec, s[62:63]
	s_waitcnt vmcnt(1)
	s_mov_b32 s77, 0
	s_branch .Lce_stores_P2
.Lce_stop_P2:
	s_mov_b64 exec, s[62:63]
.Lce_wait_all_P2:
	s_waitcnt vmcnt(0)
.Lce_stores_P2:
	s_cmp_le_u32 s75, 0
	s_cselect_b32 s6, s50, s10
	s_cselect_b32 s7, s51, s11
	global_store_dwordx4 v104, v[40:43], s[6:7] nt
	s_cmp_le_u32 s75, 1
	s_cselect_b32 s6, s50, s10
	s_cselect_b32 s7, s51, s11
	global_store_dwordx4 v105, v[44:47], s[6:7] nt
	s_cmp_le_u32 s75, 2
	s_cselect_b32 s6, s50, s10
	s_cselect_b32 s7, s51, s11
	global_store_dwordx4 v106, v[48:51], s[6:7] nt
	s_cmp_le_u32 s75, 3
	s_cselect_b32 s6, s50, s10
	s_cselect_b32 s7, s51, s11
	global_store_dwordx4 v107, v[52:55], s[6:7] nt
	s_cmp_le_u32 s75, 4
	s_cselect_b32 s6, s50, s10
	s_cselect_b32 s7, s51, s11
	global_store_dwordx4 v108, v[56:59], s[6:7] nt
	s_cmp_le_u32 s75, 5
	s_cselect_b32 s6, s50, s10
	s_cselect_b32 s7, s51, s11
	global_store_dwordx4 v109, v[60:63], s[6:7] nt
	s_cmp_le_u32 s75, 6
	s_cselect_b32 s6, s50, s10
	s_cselect_b32 s7, s51, s11
	global_store_dwordx4 v110, v[64:67], s[6:7] nt
	s_cmp_le_u32 s75, 7
	s_cselect_b32 s6, s50, s10
	s_cselect_b32 s7, s51, s11
	global_store_dwordx4 v111, v[68:71], s[6:7] nt
	s_cmp_lg_u32 s70, 0
	s_cbranch_scc1 .Lce_bar_P2
	s_cmp_lg_u32 s77, 0
	s_cbranch_scc1 .Lce_pub_P2
	s_waitcnt vmcnt(8)
	s_branch .Lce_pub2_P2
.Lce_pub_P2:
	v_mov_b32_e32 v4, -1
.Lce_pub2_P2:
	v_lshl_add_u32 v7, s71, 2, v6
	s_mov_b64 exec, 1
	ds_write_b32 v7, v4
	s_waitcnt lgkmcnt(0)
	s_mov_b64 exec, s[62:63]
.Lce_bar_P2:
	s_barrier
	v_lshl_add_u32 v7, s71, 2, v6
	ds_read_b32 v7, v7
	s_xor_b32 s71, s71, 1
	s_waitcnt lgkmcnt(0)
	v_readfirstlane_b32 s4, v7
	s_nop 3
	s_cmp_lt_u32 s4, 0x1fe00
	s_cbranch_scc1 .Lce_loop_P2
.Lce_exit_P2:
.LBB0_209:
	s_mov_b64 s[0:1], 0

.LBB0_1752:
	s_nop 0
	v_readlane_b32 s4, v242, 2
	v_readlane_b32 s6, v242, 4
	v_readlane_b32 s7, v242, 5
	s_add_u32 s0, s6, 0x14900000
	s_addc_u32 s1, s7, 0
	v_readlane_b32 s5, v242, 3
	v_writelane_b32 v242, s0, 47
	s_cmp_lt_i32 s72, 6
	s_nop 0
	v_writelane_b32 v242, s1, 48
	s_cselect_b64 s[0:1], -1, 0
	s_cmp_gt_i32 s73, 5
	s_cselect_b64 s[2:3], -1, 0
	s_and_b64 s[0:1], s[0:1], s[2:3]
	s_andn2_b64 vcc, exec, s[0:1]
	s_cbranch_vccnz .LBB0_1891
	s_and_b64 s[0:1], s[58:59], exec
	s_cselect_b32 s33, 0xb0, s84
	s_add_u32 s0, s6, 0x5400
	s_addc_u32 s1, s7, 0
	v_writelane_b32 v242, s0, 30
	v_mov_b32_e32 v149, 0
	v_lshl_add_u64 v[134:135], s[4:5], 0, v[148:149]
	v_writelane_b32 v242, s1, 31
	s_add_u32 s0, s6, 0x5500
	s_addc_u32 s1, s7, 0
	v_writelane_b32 v241, s0, 2
	s_mov_b64 s[4:5], -1
	s_nop 0
	v_writelane_b32 v241, s1, 3
	s_add_u32 s0, s6, 0x5600
	s_addc_u32 s1, s7, 0
	v_writelane_b32 v241, s0, 4
	s_nop 1
	v_writelane_b32 v241, s1, 5
	s_add_u32 s0, s6, 0x5700
	s_addc_u32 s1, s7, 0
	v_writelane_b32 v241, s0, 6
	s_nop 1
	v_writelane_b32 v241, s1, 7
	s_add_u32 s0, s6, 0x5800
	s_addc_u32 s1, s7, 0
	s_add_u32 s14, s6, 0x5900
	s_addc_u32 s15, s7, 0
	s_add_u32 s16, s6, 0x5a00
	s_addc_u32 s17, s7, 0
	s_add_u32 s18, s6, 0x5b00
	s_addc_u32 s19, s7, 0
	s_add_u32 s20, s6, 0x5c00
	s_addc_u32 s21, s7, 0
	s_add_u32 s22, s6, 0x5d00
	s_addc_u32 s23, s7, 0
	s_add_u32 s24, s6, 0x5e00
	s_addc_u32 s25, s7, 0
	s_add_u32 s26, s6, 0x5f00
	s_addc_u32 s27, s7, 0
	s_add_u32 s28, s6, 0x6000
	s_addc_u32 s29, s7, 0
	s_add_u32 s30, s6, 0x6100
	s_addc_u32 s31, s7, 0
	s_add_u32 s34, s6, 0x6200
	s_addc_u32 s35, s7, 0
	s_add_u32 s40, s6, 0x6300
	s_addc_u32 s41, s7, 0
	s_ashr_i32 s42, s33, 31
	v_writelane_b32 v241, s0, 8
	s_cmp_gt_u32 s73, 6
	s_nop 0
	v_writelane_b32 v241, s1, 9
	s_cselect_b64 s[0:1], -1, 0
	v_writelane_b32 v241, s0, 10
	s_cmp_lt_i32 s92, s33
	s_nop 0
	v_writelane_b32 v241, s1, 11
	s_cbranch_scc1 .LBB0_1787
	v_lshlrev_b32_e32 v104, 4, v0
	v_add_u32_e32 v105, 0x2000, v104
	v_add_u32_e32 v106, 0x4000, v104
	v_add_u32_e32 v107, 0x6000, v104
	v_add_u32_e32 v108, 0x8000, v104
	v_add_u32_e32 v109, 0xa000, v104
	v_add_u32_e32 v110, 0xc000, v104
	v_add_u32_e32 v111, 0xe000, v104
	v_lshrrev_b32_e32 v5, 6, v0
	v_readlane_b32 s56, v242, 43
	v_readlane_b32 s57, v242, 44
	v_readlane_b32 s60, v242, 2
	v_readlane_b32 s61, v242, 3
	v_readlane_b32 s66, v242, 4
	v_readlane_b32 s67, v242, 5
	v_readlane_b32 s68, v242, 25
	v_readfirstlane_b32 s70, v5
	v_mov_b32_e32 v2, 0
	v_mov_b32_e32 v3, 8
	v_mov_b32_e32 v6, 0x20180
	s_mov_b32 s64, 0x10478000
	s_mov_b32 s65, 0x30478000
	s_add_u32 s66, s66, 0x5400
	s_addc_u32 s67, s67, 0
	s_mul_i32 s68, s68, s84
	s_mov_b64 s[62:63], exec
	s_mov_b32 s71, 0
	s_cmp_lg_u32 s70, 0
	s_cbranch_scc1 .Lce_first_done_P5
	s_mov_b64 exec, 1
	global_atomic_add v4, v2, v3, s[56:57] sc0
	s_waitcnt vmcnt(0)
	ds_write_b32 v6, v4
	s_waitcnt lgkmcnt(0)
	s_mov_b64 exec, s[62:63]

.Lce_stop_P5:
	s_mov_b64 exec, s[62:63]
.Lce_wait_all_P5:
	s_waitcnt vmcnt(0)

.LBB0_1957:
	s_nop 0
	v_readlane_b32 s8, v242, 2
	v_readlane_b32 s10, v242, 4
	v_readlane_b32 s11, v242, 5
	s_add_u32 s2, s10, 0x1cd00000
	s_addc_u32 s3, s11, 0
	s_cmp_lt_i32 s72, 8
	s_cselect_b64 s[0:1], -1, 0
	s_cmp_gt_i32 s73, 7
	s_cselect_b64 s[4:5], -1, 0
	s_and_b64 s[0:1], s[0:1], s[4:5]
	v_readlane_b32 s9, v242, 3
	s_andn2_b64 vcc, exec, s[0:1]
	s_cbranch_vccnz .LBB0_2096
	s_and_b64 s[0:1], s[58:59], exec
	s_cselect_b32 s33, 0xf0, s84
	s_add_u32 s0, s10, 0x5400
	s_addc_u32 s1, s11, 0
	v_writelane_b32 v242, s0, 30
	v_mov_b32_e32 v149, 0
	v_lshl_add_u64 v[130:131], s[8:9], 0, v[148:149]
	v_writelane_b32 v242, s1, 31
	s_add_u32 s0, s10, 0x5500
	s_addc_u32 s1, s11, 0
	v_writelane_b32 v241, s0, 2
	s_mov_b64 s[4:5], -1
	s_nop 0
	v_writelane_b32 v241, s1, 3
	s_add_u32 s0, s10, 0x5600
	s_addc_u32 s1, s11, 0
	v_writelane_b32 v241, s0, 4
	s_nop 1
	v_writelane_b32 v241, s1, 5
	s_add_u32 s0, s10, 0x5700
	s_addc_u32 s1, s11, 0
	s_add_u32 s14, s10, 0x5800
	s_addc_u32 s15, s11, 0
	s_add_u32 s16, s10, 0x5900
	s_addc_u32 s17, s11, 0
	s_add_u32 s18, s10, 0x5a00
	s_addc_u32 s19, s11, 0
	s_add_u32 s20, s10, 0x5b00
	s_addc_u32 s21, s11, 0
	s_add_u32 s22, s10, 0x5c00
	s_addc_u32 s23, s11, 0
	s_add_u32 s24, s10, 0x5d00
	s_addc_u32 s25, s11, 0
	s_add_u32 s26, s10, 0x5e00
	s_addc_u32 s27, s11, 0
	s_add_u32 s28, s10, 0x5f00
	s_addc_u32 s29, s11, 0
	s_add_u32 s30, s10, 0x6000
	s_addc_u32 s31, s11, 0
	s_add_u32 s34, s10, 0x6100
	s_addc_u32 s35, s11, 0
	s_add_u32 s36, s10, 0x6200
	s_addc_u32 s37, s11, 0
	s_add_u32 s38, s10, 0x6300
	s_addc_u32 s39, s11, 0
	s_ashr_i32 s96, s33, 31
	v_writelane_b32 v241, s0, 6
	s_cmp_gt_u32 s73, 8
	s_nop 0
	v_writelane_b32 v241, s1, 7
	s_cselect_b64 s[0:1], -1, 0
	v_writelane_b32 v241, s0, 8
	s_cmp_lt_i32 s92, s33
	s_nop 0
	v_writelane_b32 v241, s1, 9
	s_cbranch_scc1 .LBB0_1992
	v_lshlrev_b32_e32 v104, 4, v0
	v_add_u32_e32 v105, 0x2000, v104
	v_add_u32_e32 v106, 0x4000, v104
	v_add_u32_e32 v107, 0x6000, v104
	v_add_u32_e32 v108, 0x8000, v104
	v_add_u32_e32 v109, 0xa000, v104
	v_add_u32_e32 v110, 0xc000, v104
	v_add_u32_e32 v111, 0xe000, v104
	v_lshrrev_b32_e32 v5, 6, v0
	v_readlane_b32 s56, v242, 43
	v_readlane_b32 s57, v242, 44
	v_readlane_b32 s60, v242, 2
	v_readlane_b32 s61, v242, 3
	v_readlane_b32 s66, v242, 4
	v_readlane_b32 s67, v242, 5
	v_readlane_b32 s68, v242, 25
	v_readfirstlane_b32 s70, v5
	v_mov_b32_e32 v2, 0
	v_mov_b32_e32 v3, 8
	v_mov_b32_e32 v6, 0x20180
	s_mov_b32 s64, 0x10478000
	s_mov_b32 s65, 0x30478000
	s_add_u32 s66, s66, 0x5400
	s_addc_u32 s67, s67, 0
	s_mul_i32 s68, s68, s84
	s_mov_b64 s[62:63], exec
	s_mov_b32 s71, 0
	s_cmp_lg_u32 s70, 0
	s_cbranch_scc1 .Lce_first_done_P7
	s_mov_b64 exec, 1
	global_atomic_add v4, v2, v3, s[56:57] sc0
	s_waitcnt vmcnt(0)
	ds_write_b32 v6, v4
	s_waitcnt lgkmcnt(0)
	s_mov_b64 exec, s[62:63]

.Lce_stop_P7:
	s_mov_b64 exec, s[62:63]
.Lce_wait_all_P7:
	s_waitcnt vmcnt(0)
